# scan: helper waves run at raised priority (s_setprio 3) since their load/prep/derive/M pipeline is the critical path of a chunk
# speedup vs baseline: 1.0271x; 1.0271x over previous
.Lmy_f_hlp:
	s_setprio 3
	s_cmp_eq_u32 s65, 63
	s_cbranch_scc0 .Lmy_f_hl2
	s_branch .LBB0_655

.Lmy_ck_drE_h:
	s_waitcnt lgkmcnt(0)
	s_bfe_u32 s96, s62, 0x20006
	s_and_b32 s97, s96, 1
	s_mul_i32 s97, s97, 0x2700
	s_mov_b32 s101, 0x1c000
	s_mov_b32 s100, 0x6100
	s_bitcmp0_b32 s65, 0
	s_cselect_b32 s101, 0xe000, s101
	s_cselect_b32 s100, 0x4e00, s100
	s_cmp_gt_u32 s96, 1
	s_cselect_b32 s100, s100, 0
	s_add_i32 s97, s97, s101
	s_add_i32 s97, s97, s100
	s_mov_b32 s96, s97
	v_and_b32_e32 v72, 3, v233
	v_lshrrev_b32_e32 v73, 2, v233
	v_lshlrev_b32_e32 v72, 2, v72
	v_lshl_add_u32 v72, v73, 8, v72
	v_lshl_add_u32 v72, v234, 6, v72
	s_add_i32 s97, s96, 0x1000
	v_add_u32_e32 v78, s97, v72
	v_xor_b32_e32 v79, v224, v234
	v_lshl_add_u32 v79, v79, 4, s96
	ds_read_b128 v[96:99], v79
	ds_read_b128 v[100:103], v79 offset:1024
	ds_read_b128 v[104:107], v79 offset:2048
	ds_read_b128 v[108:111], v79 offset:3072
	ds_read_b32 v80, v78
	ds_read_b32 v81, v78 offset:16
	ds_read_b32 v82, v78 offset:32
	ds_read_b32 v83, v78 offset:48
	ds_read_b32 v84, v78 offset:1024
	ds_read_b32 v85, v78 offset:1040
	ds_read_b32 v86, v78 offset:1056
	ds_read_b32 v87, v78 offset:1072
	ds_read_b32 v88, v78 offset:2048
	ds_read_b32 v89, v78 offset:2064
	ds_read_b32 v90, v78 offset:2080
	ds_read_b32 v91, v78 offset:2096
	ds_read_b32 v92, v78 offset:3072
	ds_read_b32 v93, v78 offset:3088
	ds_read_b32 v94, v78 offset:3104
	ds_read_b32 v95, v78 offset:3120
	v_lshl_add_u32 v74, v224, 2, s96
	ds_write_b32 v74, v235 offset:9728
	v_add_u32_e32 v75, -1, v233
	v_mov_b32_e32 v76, -1
	v_cndmask_b32_e64 v75, v76, v75, s[98:99]
	v_cmp_lt_u32_e64 s[100:101], 7, v233
	v_add_u32_e32 v76, -8, v233
	v_and_b32_e32 v77, 1, v234
	v_cndmask_b32_e64 v75, v75, v76, s[100:101]
	v_lshlrev_b32_e32 v77, 2, v77
	v_sub_u32_e32 v76, v75, v77
	v_lshlrev_b32_e32 v77, 2, v234
	v_sub_u32_e32 v77, v233, v77
	v_add_u32_e32 v77, -1, v77
	s_waitcnt lgkmcnt(15)
	v_mfma_f32_16x16x4_f32 v[244:247], v80, v96, 0
	v_mfma_f32_16x16x4_f32 v[240:243], v81, v97, 0
	s_waitcnt lgkmcnt(14)
	v_mfma_f32_16x16x4_f32 v[244:247], v82, v98, v[244:247]
	s_waitcnt lgkmcnt(13)
	v_mfma_f32_16x16x4_f32 v[240:243], v83, v99, v[240:243]
	s_waitcnt lgkmcnt(12)
	v_mfma_f32_16x16x4_f32 v[244:247], v84, v100, v[244:247]
	s_waitcnt lgkmcnt(11)
	v_mfma_f32_16x16x4_f32 v[240:243], v85, v101, v[240:243]
	s_waitcnt lgkmcnt(10)
	v_mfma_f32_16x16x4_f32 v[244:247], v86, v102, v[244:247]
	s_waitcnt lgkmcnt(9)
	v_mfma_f32_16x16x4_f32 v[240:243], v87, v103, v[240:243]
	s_waitcnt lgkmcnt(8)
	v_mfma_f32_16x16x4_f32 v[244:247], v88, v104, v[244:247]
	s_waitcnt lgkmcnt(7)
	v_mfma_f32_16x16x4_f32 v[240:243], v89, v105, v[240:243]
	s_waitcnt lgkmcnt(6)
	v_mfma_f32_16x16x4_f32 v[244:247], v90, v106, v[244:247]
	s_waitcnt lgkmcnt(5)
	v_mfma_f32_16x16x4_f32 v[240:243], v91, v107, v[240:243]
	s_waitcnt lgkmcnt(4)
	v_mfma_f32_16x16x4_f32 v[244:247], v92, v108, v[244:247]
	s_waitcnt lgkmcnt(3)
	v_mfma_f32_16x16x4_f32 v[240:243], v93, v109, v[240:243]
	s_waitcnt lgkmcnt(2)
	v_mfma_f32_16x16x4_f32 v[244:247], v94, v110, v[244:247]
	s_waitcnt lgkmcnt(1)
	v_mfma_f32_16x16x4_f32 v[240:243], v95, v111, v[240:243]
	s_nop 9
	v_add_f32_e32 v244, v244, v240
	v_add_f32_e32 v245, v245, v241
	v_add_f32_e32 v246, v246, v242
	v_add_f32_e32 v247, v247, v243
	v_cmp_le_i32_e64 s[96:97], 0, v76
	v_cmp_le_i32_e64 s[100:101], 1, v76
	s_nop 0
	v_cndmask_b32_e64 v128, 0, v244, s[96:97]
	v_cndmask_b32_e64 v129, 0, v245, s[100:101]
	v_cmp_le_i32_e64 s[96:97], 2, v76
	v_cmp_le_i32_e64 s[100:101], 3, v76
	s_nop 0
	v_cndmask_b32_e64 v130, 0, v246, s[96:97]
	v_cndmask_b32_e64 v131, 0, v247, s[100:101]
	s_bfe_u32 s96, s62, 0x20006
	s_and_b32 s97, s96, 1
	s_mul_i32 s97, s97, 0x2700
	s_mov_b32 s101, 0x1c000
	s_mov_b32 s100, 0x6100
	s_bitcmp0_b32 s65, 0
	s_cselect_b32 s101, 0xe000, s101
	s_cselect_b32 s100, 0x4e00, s100
	s_cmp_gt_u32 s96, 1
	s_cselect_b32 s100, s100, 0
	s_add_i32 s97, s97, s101
	s_add_i32 s97, s97, s100
	v_xor_b32_e32 v74, v224, v234
	v_lshl_add_u32 v74, v74, 4, s97
	ds_write_b128 v74, v[128:131] offset:8448
	v_lshlrev_b32_e32 v75, 7, v234
	v_lshl_add_u32 v75, v233, 2, v75
	v_add_u32_e32 v75, s97, v75
	v_cmp_le_i32_e64 s[96:97], 0, v77
	v_cmp_le_i32_e64 s[100:101], 1, v77
	s_nop 0
	v_cndmask_b32_e64 v132, 0, v244, s[96:97]
	v_cndmask_b32_e64 v133, 0, v245, s[100:101]
	v_cmp_le_i32_e64 s[96:97], 2, v77
	v_cmp_le_i32_e64 s[100:101], 3, v77
	s_nop 0
	v_cndmask_b32_e64 v134, 0, v246, s[96:97]
	v_cndmask_b32_e64 v135, 0, v247, s[100:101]
	s_mov_b64 exec, 0x00ff00ff
	ds_write_b32 v75, v132 offset:9472
	ds_write_b32 v75, v133 offset:9504
	ds_write_b32 v75, v134 offset:9536
	ds_write_b32 v75, v135 offset:9568
	s_mov_b64 exec, -1
	s_setprio 0
	s_branch .LBB0_655
	s_nop 0
	s_nop 0
	s_nop 0
	s_nop 0
	s_nop 0
	s_nop 0
	s_nop 0
	s_nop 0
	s_nop 0
	s_nop 0
	s_nop 0
	s_nop 0
	s_nop 0
	s_nop 0
	s_nop 0
	s_nop 0
	s_nop 0
	s_nop 0
	s_nop 0
	s_nop 0
	s_nop 0
	s_nop 0
	s_nop 0
	s_nop 0
	s_nop 0
	s_nop 0
	s_nop 0
	s_nop 0
	s_nop 0
	s_nop 0
	s_nop 0
	s_nop 0
	s_nop 0
	s_nop 0
	s_nop 0
	s_nop 0
	s_nop 0
	s_nop 0
	s_nop 0
	s_nop 0
	s_nop 0
	s_nop 0
	s_nop 0
	s_nop 0
	s_nop 0
	s_nop 0
	s_nop 0
	s_nop 0
	s_nop 0
	s_nop 0
	s_nop 0
	s_nop 0
	s_nop 0
	s_nop 0
	s_nop 0
	s_nop 0
	s_nop 0
	s_nop 0
	s_nop 0
	s_nop 0
	s_nop 0
	s_nop 0
